# SUM pass: all 27 loads per thread issued up front (one round trip instead of three), saddr addressing
# baseline (speedup 1.0000x reference)
.LBB0_969:
	s_or_b64 exec, exec, s[6:7]
	s_mov_b64 s[8:9], s[46:47]
	s_waitcnt lgkmcnt(0)
	v_mov_b32_e32 v0, v195
	v_readlane_b32 s0, v245, 0
	s_barrier
	s_nop 0
	v_add_u32_e32 v52, s0, v0
	v_cmp_gt_i32_e32 vcc, s57, v52
	s_and_saveexec_b64 s[6:7], vcc
	s_cbranch_execz .LBB0_984
	s_load_dwordx2 s[0:1], s[8:9], 0x100
	v_readlane_b32 s3, v243, 19
	v_ashrrev_i32_e32 v168, 7, v52
	s_mov_b32 s14, 0x3800
	v_lshl_add_u32 v169, v0, 3, s3
	v_and_b32_e32 v169, 0x3f8, v169
	v_lshlrev_b32_e32 v169, 1, v169
	v_mad_u32_u24 v168, v168, s68, v169
	v_add_u32_e32 v170, s14, v168
	v_add_u32_e32 v171, 0x1200000, v170
	v_add_u32_e32 v172, 0x1200000, v171
	v_add_u32_e32 v173, 0x1200000, v172
	v_add_u32_e32 v174, 0x1200000, v173
	v_add_u32_e32 v175, 0x1200000, v174
	v_add_u32_e32 v176, 0x1200000, v175
	v_add_u32_e32 v177, 0x1200000, v176
	v_add_u32_e32 v178, 0x1200000, v177
	s_waitcnt lgkmcnt(0)
	s_add_u32 s8, s0, 0x7670000
	s_addc_u32 s9, s1, 0
	global_load_dwordx4 v[60:63], v170, s[8:9] offset:-2048
	global_load_dwordx4 v[64:67], v170, s[8:9]
	global_load_dwordx4 v[68:71], v170, s[8:9] offset:2048
	global_load_dwordx4 v[72:75], v171, s[8:9] offset:-2048
	global_load_dwordx4 v[76:79], v171, s[8:9]
	global_load_dwordx4 v[80:83], v171, s[8:9] offset:2048
	global_load_dwordx4 v[84:87], v172, s[8:9] offset:-2048
	global_load_dwordx4 v[88:91], v172, s[8:9]
	global_load_dwordx4 v[92:95], v172, s[8:9] offset:2048
	global_load_dwordx4 v[96:99], v173, s[8:9] offset:-2048
	global_load_dwordx4 v[100:103], v173, s[8:9]
	global_load_dwordx4 v[104:107], v173, s[8:9] offset:2048
	global_load_dwordx4 v[108:111], v174, s[8:9] offset:-2048
	global_load_dwordx4 v[112:115], v174, s[8:9]
	global_load_dwordx4 v[116:119], v174, s[8:9] offset:2048
	global_load_dwordx4 v[120:123], v175, s[8:9] offset:-2048
	global_load_dwordx4 v[124:127], v175, s[8:9]
	global_load_dwordx4 v[128:131], v175, s[8:9] offset:2048
	global_load_dwordx4 v[132:135], v176, s[8:9] offset:-2048
	global_load_dwordx4 v[136:139], v176, s[8:9]
	global_load_dwordx4 v[140:143], v176, s[8:9] offset:2048
	global_load_dwordx4 v[144:147], v177, s[8:9] offset:-2048
	global_load_dwordx4 v[148:151], v177, s[8:9]
	global_load_dwordx4 v[152:155], v177, s[8:9] offset:2048
	global_load_dwordx4 v[156:159], v178, s[8:9] offset:-2048
	global_load_dwordx4 v[160:163], v178, s[8:9]
	global_load_dwordx4 v[164:167], v178, s[8:9] offset:2048
	s_waitcnt vmcnt(24)
	v_lshlrev_b32_e32 v180, 16, v60
	v_lshlrev_b32_e32 v181, 16, v64
	v_and_b32_e32 v182, 0xffff0000, v60
	v_and_b32_e32 v183, 0xffff0000, v64
	v_add_f32_e32 v180, v180, v181
	v_add_f32_e32 v182, v182, v183
	v_lshlrev_b32_e32 v181, 16, v68
	v_and_b32_e32 v183, 0xffff0000, v68
	v_add_f32_e32 v180, v180, v181
	v_add_f32_e32 v182, v182, v183
	v_cvt_pk_bf16_f32 v60, v180, v182
	v_lshlrev_b32_e32 v180, 16, v61
	v_lshlrev_b32_e32 v181, 16, v65
	v_and_b32_e32 v182, 0xffff0000, v61
	v_and_b32_e32 v183, 0xffff0000, v65
	v_add_f32_e32 v180, v180, v181
	v_add_f32_e32 v182, v182, v183
	v_lshlrev_b32_e32 v181, 16, v69
	v_and_b32_e32 v183, 0xffff0000, v69
	v_add_f32_e32 v180, v180, v181
	v_add_f32_e32 v182, v182, v183
	v_cvt_pk_bf16_f32 v61, v180, v182
	v_lshlrev_b32_e32 v180, 16, v62
	v_lshlrev_b32_e32 v181, 16, v66
	v_and_b32_e32 v182, 0xffff0000, v62
	v_and_b32_e32 v183, 0xffff0000, v66
	v_add_f32_e32 v180, v180, v181
	v_add_f32_e32 v182, v182, v183
	v_lshlrev_b32_e32 v181, 16, v70
	v_and_b32_e32 v183, 0xffff0000, v70
	v_add_f32_e32 v180, v180, v181
	v_add_f32_e32 v182, v182, v183
	v_cvt_pk_bf16_f32 v62, v180, v182
	v_lshlrev_b32_e32 v180, 16, v63
	v_lshlrev_b32_e32 v181, 16, v67
	v_and_b32_e32 v182, 0xffff0000, v63
	v_and_b32_e32 v183, 0xffff0000, v67
	v_add_f32_e32 v180, v180, v181
	v_add_f32_e32 v182, v182, v183
	v_lshlrev_b32_e32 v181, 16, v71
	v_and_b32_e32 v183, 0xffff0000, v71
	v_add_f32_e32 v180, v180, v181
	v_add_f32_e32 v182, v182, v183
	v_cvt_pk_bf16_f32 v63, v180, v182
	global_store_dwordx4 v170, v[60:63], s[8:9] offset:-2048
	s_waitcnt vmcnt(22)
	v_lshlrev_b32_e32 v180, 16, v72
	v_lshlrev_b32_e32 v181, 16, v76
	v_and_b32_e32 v182, 0xffff0000, v72
	v_and_b32_e32 v183, 0xffff0000, v76
	v_add_f32_e32 v180, v180, v181
	v_add_f32_e32 v182, v182, v183
	v_lshlrev_b32_e32 v181, 16, v80
	v_and_b32_e32 v183, 0xffff0000, v80
	v_add_f32_e32 v180, v180, v181
	v_add_f32_e32 v182, v182, v183
	v_cvt_pk_bf16_f32 v72, v180, v182
	v_lshlrev_b32_e32 v180, 16, v73
	v_lshlrev_b32_e32 v181, 16, v77
	v_and_b32_e32 v182, 0xffff0000, v73
	v_and_b32_e32 v183, 0xffff0000, v77
	v_add_f32_e32 v180, v180, v181
	v_add_f32_e32 v182, v182, v183
	v_lshlrev_b32_e32 v181, 16, v81
	v_and_b32_e32 v183, 0xffff0000, v81
	v_add_f32_e32 v180, v180, v181
	v_add_f32_e32 v182, v182, v183
	v_cvt_pk_bf16_f32 v73, v180, v182
	v_lshlrev_b32_e32 v180, 16, v74
	v_lshlrev_b32_e32 v181, 16, v78
	v_and_b32_e32 v182, 0xffff0000, v74
	v_and_b32_e32 v183, 0xffff0000, v78
	v_add_f32_e32 v180, v180, v181
	v_add_f32_e32 v182, v182, v183
	v_lshlrev_b32_e32 v181, 16, v82
	v_and_b32_e32 v183, 0xffff0000, v82
	v_add_f32_e32 v180, v180, v181
	v_add_f32_e32 v182, v182, v183
	v_cvt_pk_bf16_f32 v74, v180, v182
	v_lshlrev_b32_e32 v180, 16, v75
	v_lshlrev_b32_e32 v181, 16, v79
	v_and_b32_e32 v182, 0xffff0000, v75
	v_and_b32_e32 v183, 0xffff0000, v79
	v_add_f32_e32 v180, v180, v181
	v_add_f32_e32 v182, v182, v183
	v_lshlrev_b32_e32 v181, 16, v83
	v_and_b32_e32 v183, 0xffff0000, v83
	v_add_f32_e32 v180, v180, v181
	v_add_f32_e32 v182, v182, v183
	v_cvt_pk_bf16_f32 v75, v180, v182
	global_store_dwordx4 v171, v[72:75], s[8:9] offset:-2048
	s_waitcnt vmcnt(20)
	v_lshlrev_b32_e32 v180, 16, v84
	v_lshlrev_b32_e32 v181, 16, v88
	v_and_b32_e32 v182, 0xffff0000, v84
	v_and_b32_e32 v183, 0xffff0000, v88
	v_add_f32_e32 v180, v180, v181
	v_add_f32_e32 v182, v182, v183
	v_lshlrev_b32_e32 v181, 16, v92
	v_and_b32_e32 v183, 0xffff0000, v92
	v_add_f32_e32 v180, v180, v181
	v_add_f32_e32 v182, v182, v183
	v_cvt_pk_bf16_f32 v84, v180, v182
	v_lshlrev_b32_e32 v180, 16, v85
	v_lshlrev_b32_e32 v181, 16, v89
	v_and_b32_e32 v182, 0xffff0000, v85
	v_and_b32_e32 v183, 0xffff0000, v89
	v_add_f32_e32 v180, v180, v181
	v_add_f32_e32 v182, v182, v183
	v_lshlrev_b32_e32 v181, 16, v93
	v_and_b32_e32 v183, 0xffff0000, v93
	v_add_f32_e32 v180, v180, v181
	v_add_f32_e32 v182, v182, v183
	v_cvt_pk_bf16_f32 v85, v180, v182
	v_lshlrev_b32_e32 v180, 16, v86
	v_lshlrev_b32_e32 v181, 16, v90
	v_and_b32_e32 v182, 0xffff0000, v86
	v_and_b32_e32 v183, 0xffff0000, v90
	v_add_f32_e32 v180, v180, v181
	v_add_f32_e32 v182, v182, v183
	v_lshlrev_b32_e32 v181, 16, v94
	v_and_b32_e32 v183, 0xffff0000, v94
	v_add_f32_e32 v180, v180, v181
	v_add_f32_e32 v182, v182, v183
	v_cvt_pk_bf16_f32 v86, v180, v182
	v_lshlrev_b32_e32 v180, 16, v87
	v_lshlrev_b32_e32 v181, 16, v91
	v_and_b32_e32 v182, 0xffff0000, v87
	v_and_b32_e32 v183, 0xffff0000, v91
	v_add_f32_e32 v180, v180, v181
	v_add_f32_e32 v182, v182, v183
	v_lshlrev_b32_e32 v181, 16, v95
	v_and_b32_e32 v183, 0xffff0000, v95
	v_add_f32_e32 v180, v180, v181
	v_add_f32_e32 v182, v182, v183
	v_cvt_pk_bf16_f32 v87, v180, v182
	global_store_dwordx4 v172, v[84:87], s[8:9] offset:-2048
	s_waitcnt vmcnt(18)
	v_lshlrev_b32_e32 v180, 16, v96
	v_lshlrev_b32_e32 v181, 16, v100
	v_and_b32_e32 v182, 0xffff0000, v96
	v_and_b32_e32 v183, 0xffff0000, v100
	v_add_f32_e32 v180, v180, v181
	v_add_f32_e32 v182, v182, v183
	v_lshlrev_b32_e32 v181, 16, v104
	v_and_b32_e32 v183, 0xffff0000, v104
	v_add_f32_e32 v180, v180, v181
	v_add_f32_e32 v182, v182, v183
	v_cvt_pk_bf16_f32 v96, v180, v182
	v_lshlrev_b32_e32 v180, 16, v97
	v_lshlrev_b32_e32 v181, 16, v101
	v_and_b32_e32 v182, 0xffff0000, v97
	v_and_b32_e32 v183, 0xffff0000, v101
	v_add_f32_e32 v180, v180, v181
	v_add_f32_e32 v182, v182, v183
	v_lshlrev_b32_e32 v181, 16, v105
	v_and_b32_e32 v183, 0xffff0000, v105
	v_add_f32_e32 v180, v180, v181
	v_add_f32_e32 v182, v182, v183
	v_cvt_pk_bf16_f32 v97, v180, v182
	v_lshlrev_b32_e32 v180, 16, v98
	v_lshlrev_b32_e32 v181, 16, v102
	v_and_b32_e32 v182, 0xffff0000, v98
	v_and_b32_e32 v183, 0xffff0000, v102
	v_add_f32_e32 v180, v180, v181
	v_add_f32_e32 v182, v182, v183
	v_lshlrev_b32_e32 v181, 16, v106
	v_and_b32_e32 v183, 0xffff0000, v106
	v_add_f32_e32 v180, v180, v181
	v_add_f32_e32 v182, v182, v183
	v_cvt_pk_bf16_f32 v98, v180, v182
	v_lshlrev_b32_e32 v180, 16, v99
	v_lshlrev_b32_e32 v181, 16, v103
	v_and_b32_e32 v182, 0xffff0000, v99
	v_and_b32_e32 v183, 0xffff0000, v103
	v_add_f32_e32 v180, v180, v181
	v_add_f32_e32 v182, v182, v183
	v_lshlrev_b32_e32 v181, 16, v107
	v_and_b32_e32 v183, 0xffff0000, v107
	v_add_f32_e32 v180, v180, v181
	v_add_f32_e32 v182, v182, v183
	v_cvt_pk_bf16_f32 v99, v180, v182
	global_store_dwordx4 v173, v[96:99], s[8:9] offset:-2048
	s_waitcnt vmcnt(16)
	v_lshlrev_b32_e32 v180, 16, v108
	v_lshlrev_b32_e32 v181, 16, v112
	v_and_b32_e32 v182, 0xffff0000, v108
	v_and_b32_e32 v183, 0xffff0000, v112
	v_add_f32_e32 v180, v180, v181
	v_add_f32_e32 v182, v182, v183
	v_lshlrev_b32_e32 v181, 16, v116
	v_and_b32_e32 v183, 0xffff0000, v116
	v_add_f32_e32 v180, v180, v181
	v_add_f32_e32 v182, v182, v183
	v_cvt_pk_bf16_f32 v108, v180, v182
	v_lshlrev_b32_e32 v180, 16, v109
	v_lshlrev_b32_e32 v181, 16, v113
	v_and_b32_e32 v182, 0xffff0000, v109
	v_and_b32_e32 v183, 0xffff0000, v113
	v_add_f32_e32 v180, v180, v181
	v_add_f32_e32 v182, v182, v183
	v_lshlrev_b32_e32 v181, 16, v117
	v_and_b32_e32 v183, 0xffff0000, v117
	v_add_f32_e32 v180, v180, v181
	v_add_f32_e32 v182, v182, v183
	v_cvt_pk_bf16_f32 v109, v180, v182
	v_lshlrev_b32_e32 v180, 16, v110
	v_lshlrev_b32_e32 v181, 16, v114
	v_and_b32_e32 v182, 0xffff0000, v110
	v_and_b32_e32 v183, 0xffff0000, v114
	v_add_f32_e32 v180, v180, v181
	v_add_f32_e32 v182, v182, v183
	v_lshlrev_b32_e32 v181, 16, v118
	v_and_b32_e32 v183, 0xffff0000, v118
	v_add_f32_e32 v180, v180, v181
	v_add_f32_e32 v182, v182, v183
	v_cvt_pk_bf16_f32 v110, v180, v182
	v_lshlrev_b32_e32 v180, 16, v111
	v_lshlrev_b32_e32 v181, 16, v115
	v_and_b32_e32 v182, 0xffff0000, v111
	v_and_b32_e32 v183, 0xffff0000, v115
	v_add_f32_e32 v180, v180, v181
	v_add_f32_e32 v182, v182, v183
	v_lshlrev_b32_e32 v181, 16, v119
	v_and_b32_e32 v183, 0xffff0000, v119
	v_add_f32_e32 v180, v180, v181
	v_add_f32_e32 v182, v182, v183
	v_cvt_pk_bf16_f32 v111, v180, v182
	global_store_dwordx4 v174, v[108:111], s[8:9] offset:-2048
	s_waitcnt vmcnt(14)
	v_lshlrev_b32_e32 v180, 16, v120
	v_lshlrev_b32_e32 v181, 16, v124
	v_and_b32_e32 v182, 0xffff0000, v120
	v_and_b32_e32 v183, 0xffff0000, v124
	v_add_f32_e32 v180, v180, v181
	v_add_f32_e32 v182, v182, v183
	v_lshlrev_b32_e32 v181, 16, v128
	v_and_b32_e32 v183, 0xffff0000, v128
	v_add_f32_e32 v180, v180, v181
	v_add_f32_e32 v182, v182, v183
	v_cvt_pk_bf16_f32 v120, v180, v182
	v_lshlrev_b32_e32 v180, 16, v121
	v_lshlrev_b32_e32 v181, 16, v125
	v_and_b32_e32 v182, 0xffff0000, v121
	v_and_b32_e32 v183, 0xffff0000, v125
	v_add_f32_e32 v180, v180, v181
	v_add_f32_e32 v182, v182, v183
	v_lshlrev_b32_e32 v181, 16, v129
	v_and_b32_e32 v183, 0xffff0000, v129
	v_add_f32_e32 v180, v180, v181
	v_add_f32_e32 v182, v182, v183
	v_cvt_pk_bf16_f32 v121, v180, v182
	v_lshlrev_b32_e32 v180, 16, v122
	v_lshlrev_b32_e32 v181, 16, v126
	v_and_b32_e32 v182, 0xffff0000, v122
	v_and_b32_e32 v183, 0xffff0000, v126
	v_add_f32_e32 v180, v180, v181
	v_add_f32_e32 v182, v182, v183
	v_lshlrev_b32_e32 v181, 16, v130
	v_and_b32_e32 v183, 0xffff0000, v130
	v_add_f32_e32 v180, v180, v181
	v_add_f32_e32 v182, v182, v183
	v_cvt_pk_bf16_f32 v122, v180, v182
	v_lshlrev_b32_e32 v180, 16, v123
	v_lshlrev_b32_e32 v181, 16, v127
	v_and_b32_e32 v182, 0xffff0000, v123
	v_and_b32_e32 v183, 0xffff0000, v127
	v_add_f32_e32 v180, v180, v181
	v_add_f32_e32 v182, v182, v183
	v_lshlrev_b32_e32 v181, 16, v131
	v_and_b32_e32 v183, 0xffff0000, v131
	v_add_f32_e32 v180, v180, v181
	v_add_f32_e32 v182, v182, v183
	v_cvt_pk_bf16_f32 v123, v180, v182
	global_store_dwordx4 v175, v[120:123], s[8:9] offset:-2048
	s_waitcnt vmcnt(12)
	v_lshlrev_b32_e32 v180, 16, v132
	v_lshlrev_b32_e32 v181, 16, v136
	v_and_b32_e32 v182, 0xffff0000, v132
	v_and_b32_e32 v183, 0xffff0000, v136
	v_add_f32_e32 v180, v180, v181
	v_add_f32_e32 v182, v182, v183
	v_lshlrev_b32_e32 v181, 16, v140
	v_and_b32_e32 v183, 0xffff0000, v140
	v_add_f32_e32 v180, v180, v181
	v_add_f32_e32 v182, v182, v183
	v_cvt_pk_bf16_f32 v132, v180, v182
	v_lshlrev_b32_e32 v180, 16, v133
	v_lshlrev_b32_e32 v181, 16, v137
	v_and_b32_e32 v182, 0xffff0000, v133
	v_and_b32_e32 v183, 0xffff0000, v137
	v_add_f32_e32 v180, v180, v181
	v_add_f32_e32 v182, v182, v183
	v_lshlrev_b32_e32 v181, 16, v141
	v_and_b32_e32 v183, 0xffff0000, v141
	v_add_f32_e32 v180, v180, v181
	v_add_f32_e32 v182, v182, v183
	v_cvt_pk_bf16_f32 v133, v180, v182
	v_lshlrev_b32_e32 v180, 16, v134
	v_lshlrev_b32_e32 v181, 16, v138
	v_and_b32_e32 v182, 0xffff0000, v134
	v_and_b32_e32 v183, 0xffff0000, v138
	v_add_f32_e32 v180, v180, v181
	v_add_f32_e32 v182, v182, v183
	v_lshlrev_b32_e32 v181, 16, v142
	v_and_b32_e32 v183, 0xffff0000, v142
	v_add_f32_e32 v180, v180, v181
	v_add_f32_e32 v182, v182, v183
	v_cvt_pk_bf16_f32 v134, v180, v182
	v_lshlrev_b32_e32 v180, 16, v135
	v_lshlrev_b32_e32 v181, 16, v139
	v_and_b32_e32 v182, 0xffff0000, v135
	v_and_b32_e32 v183, 0xffff0000, v139
	v_add_f32_e32 v180, v180, v181
	v_add_f32_e32 v182, v182, v183
	v_lshlrev_b32_e32 v181, 16, v143
	v_and_b32_e32 v183, 0xffff0000, v143
	v_add_f32_e32 v180, v180, v181
	v_add_f32_e32 v182, v182, v183
	v_cvt_pk_bf16_f32 v135, v180, v182
	global_store_dwordx4 v176, v[132:135], s[8:9] offset:-2048
	s_waitcnt vmcnt(10)
	v_lshlrev_b32_e32 v180, 16, v144
	v_lshlrev_b32_e32 v181, 16, v148
	v_and_b32_e32 v182, 0xffff0000, v144
	v_and_b32_e32 v183, 0xffff0000, v148
	v_add_f32_e32 v180, v180, v181
	v_add_f32_e32 v182, v182, v183
	v_lshlrev_b32_e32 v181, 16, v152
	v_and_b32_e32 v183, 0xffff0000, v152
	v_add_f32_e32 v180, v180, v181
	v_add_f32_e32 v182, v182, v183
	v_cvt_pk_bf16_f32 v144, v180, v182
	v_lshlrev_b32_e32 v180, 16, v145
	v_lshlrev_b32_e32 v181, 16, v149
	v_and_b32_e32 v182, 0xffff0000, v145
	v_and_b32_e32 v183, 0xffff0000, v149
	v_add_f32_e32 v180, v180, v181
	v_add_f32_e32 v182, v182, v183
	v_lshlrev_b32_e32 v181, 16, v153
	v_and_b32_e32 v183, 0xffff0000, v153
	v_add_f32_e32 v180, v180, v181
	v_add_f32_e32 v182, v182, v183
	v_cvt_pk_bf16_f32 v145, v180, v182
	v_lshlrev_b32_e32 v180, 16, v146
	v_lshlrev_b32_e32 v181, 16, v150
	v_and_b32_e32 v182, 0xffff0000, v146
	v_and_b32_e32 v183, 0xffff0000, v150
	v_add_f32_e32 v180, v180, v181
	v_add_f32_e32 v182, v182, v183
	v_lshlrev_b32_e32 v181, 16, v154
	v_and_b32_e32 v183, 0xffff0000, v154
	v_add_f32_e32 v180, v180, v181
	v_add_f32_e32 v182, v182, v183
	v_cvt_pk_bf16_f32 v146, v180, v182
	v_lshlrev_b32_e32 v180, 16, v147
	v_lshlrev_b32_e32 v181, 16, v151
	v_and_b32_e32 v182, 0xffff0000, v147
	v_and_b32_e32 v183, 0xffff0000, v151
	v_add_f32_e32 v180, v180, v181
	v_add_f32_e32 v182, v182, v183
	v_lshlrev_b32_e32 v181, 16, v155
	v_and_b32_e32 v183, 0xffff0000, v155
	v_add_f32_e32 v180, v180, v181
	v_add_f32_e32 v182, v182, v183
	v_cvt_pk_bf16_f32 v147, v180, v182
	global_store_dwordx4 v177, v[144:147], s[8:9] offset:-2048
	s_waitcnt vmcnt(8)
	s_cmp_ge_u32 s2, 0x80
	s_cbranch_scc1 .Lsum_done
	v_lshlrev_b32_e32 v180, 16, v156
	v_lshlrev_b32_e32 v181, 16, v160
	v_and_b32_e32 v182, 0xffff0000, v156
	v_and_b32_e32 v183, 0xffff0000, v160
	v_add_f32_e32 v180, v180, v181
	v_add_f32_e32 v182, v182, v183
	v_lshlrev_b32_e32 v181, 16, v164
	v_and_b32_e32 v183, 0xffff0000, v164
	v_add_f32_e32 v180, v180, v181
	v_add_f32_e32 v182, v182, v183
	v_cvt_pk_bf16_f32 v156, v180, v182
	v_lshlrev_b32_e32 v180, 16, v157
	v_lshlrev_b32_e32 v181, 16, v161
	v_and_b32_e32 v182, 0xffff0000, v157
	v_and_b32_e32 v183, 0xffff0000, v161
	v_add_f32_e32 v180, v180, v181
	v_add_f32_e32 v182, v182, v183
	v_lshlrev_b32_e32 v181, 16, v165
	v_and_b32_e32 v183, 0xffff0000, v165
	v_add_f32_e32 v180, v180, v181
	v_add_f32_e32 v182, v182, v183
	v_cvt_pk_bf16_f32 v157, v180, v182
	v_lshlrev_b32_e32 v180, 16, v158
	v_lshlrev_b32_e32 v181, 16, v162
	v_and_b32_e32 v182, 0xffff0000, v158
	v_and_b32_e32 v183, 0xffff0000, v162
	v_add_f32_e32 v180, v180, v181
	v_add_f32_e32 v182, v182, v183
	v_lshlrev_b32_e32 v181, 16, v166
	v_and_b32_e32 v183, 0xffff0000, v166
	v_add_f32_e32 v180, v180, v181
	v_add_f32_e32 v182, v182, v183
	v_cvt_pk_bf16_f32 v158, v180, v182
	v_lshlrev_b32_e32 v180, 16, v159
	v_lshlrev_b32_e32 v181, 16, v163
	v_and_b32_e32 v182, 0xffff0000, v159
	v_and_b32_e32 v183, 0xffff0000, v163
	v_add_f32_e32 v180, v180, v181
	v_add_f32_e32 v182, v182, v183
	v_lshlrev_b32_e32 v181, 16, v167
	v_and_b32_e32 v183, 0xffff0000, v167
	v_add_f32_e32 v180, v180, v181
	v_add_f32_e32 v182, v182, v183
	v_cvt_pk_bf16_f32 v159, v180, v182
	global_store_dwordx4 v178, v[156:159], s[8:9] offset:-2048
.Lsum_done:
.LBB0_984:
	s_or_b64 exec, exec, s[6:7]
	s_mov_b64 s[8:9], s[46:47]
	s_getreg_b32 s0, hwreg(HW_REG_XCC_ID, 0, 4)
	s_waitcnt vmcnt(0)
	s_barrier
	s_and_saveexec_b64 s[6:7], s[82:83]
	s_cbranch_execz .LBB0_1036
	v_readlane_b32 s1, v243, 21
	s_load_dwordx2 s[8:9], s[8:9], 0x100
	s_waitcnt vmcnt(0) expcnt(0) lgkmcnt(0)
	v_mov_b32_e32 v0, s1
	ds_read_b32 v2, v0
	v_readlane_b32 s1, v243, 22
	s_and_b32 s0, s0, 15
	s_waitcnt lgkmcnt(0)
	v_cmp_ne_u32_e32 vcc, 0, v2
	v_mov_b32_e32 v0, s1
	ds_read_b32 v0, v0
	s_cbranch_vccnz .LBB0_1000
	s_add_u32 s10, s8, 0x11080200
	s_addc_u32 s11, s9, 0
	s_add_u32 s12, s8, 0x11080400
	s_addc_u32 s13, s9, 0
	s_add_u32 s14, s8, 0x11080500
	s_addc_u32 s15, s9, 0
	s_add_u32 s16, s8, 0x11080600
	s_addc_u32 s17, s9, 0
	s_add_u32 s18, s8, 0x11080700
	s_addc_u32 s19, s9, 0
	s_add_u32 s20, s8, 0x11080800
	s_addc_u32 s21, s9, 0
	s_add_u32 s22, s8, 0x11080900
	s_addc_u32 s23, s9, 0
	s_add_u32 s24, s8, 0x11080a00
	s_addc_u32 s25, s9, 0
	s_add_u32 s26, s8, 0x11080b00
	s_addc_u32 s27, s9, 0
	s_add_u32 s28, s8, 0x11080c00
	s_addc_u32 s29, s9, 0
	s_add_u32 s30, s8, 0x11080d00
	s_addc_u32 s31, s9, 0
	s_add_u32 s34, s8, 0x11080e00
	s_addc_u32 s35, s9, 0
	s_add_u32 s36, s8, 0x11080f00
	s_addc_u32 s37, s9, 0
	s_add_u32 s38, s8, 0x11081000
	s_addc_u32 s39, s9, 0
	s_add_u32 s40, s8, 0x11081100
	s_addc_u32 s41, s9, 0
	s_add_u32 s42, s8, 0x11081200
	s_addc_u32 s43, s9, 0
	s_add_u32 s44, s8, 0x11081300
	s_addc_u32 s45, s9, 0
	s_mov_b32 s1, 1
	s_branch .LBB0_988
